# GLU epilogue: glu_b vectors loaded once, each step's silu(gate) load issued one step ahead (double buffer) instead of 16 load-wait-use round trips
# speedup vs baseline: 1.0156x; 1.0156x over previous
; DI int opaque_tid() { int t = threadIdx.x; asm volatile("" : "+v"(t)); return t; }
; template <int NT2>
; DI void glu_prologue(const Params& p, char* lds, int l, int tile0, int tile1) {
;     const int tid = opaque_tid(), lane = tid & 63, wid = tid >> 6, l15 = lane & 15, quad = lane >> 4;
;     __syncthreads();
; #pragma unroll
;     for (int tt = 0; tt < NT2; ++tt) {
;         const int tile = tt ? tile1 : tile0;
;         char* Ys = lds + tt * 33792;
;         const bf16_t* ysg = WS_PTR(const bf16_t, OFF_YS) + (size_t)tile * 64 * 256;
; #pragma unroll
;         for (int i = 0; i < 4; ++i) {
;             const int idx = tid + NTHR * i, row = idx >> 5, c16 = idx & 31;
;             *(u32x4*)(Ys + row * 528 + c16 * 16) = *(const u32x4*)(ysg + (size_t)row * 256 + c16 * 8);
;         }
;     }
;     __syncthreads();
;     f32x4 acc[NT2][4][2];
; #pragma unroll
;     for (int tt = 0; tt < NT2; ++tt)
; #pragma unroll
;         for (int mt = 0; mt < 4; ++mt) { acc[tt][mt][0] = (f32x4){0.f, 0.f, 0.f, 0.f}; acc[tt][mt][1] = (f32x4){0.f, 0.f, 0.f, 0.f}; }
.LBB0_90:
	s_and_b64 vcc, exec, s[6:7]
	s_cbranch_vccz .LBB0_94
	s_ashr_i32 s35, s34, 31
	v_mov_b32_e32 v78, v212
	s_lshl_b64 s[8:9], s[34:35], 15
	v_readlane_b32 s40, v244, 46
	s_add_u32 s6, s40, s8
	v_lshlrev_b32_e32 v0, 4, v78
	v_ashrrev_i32_e32 v8, 5, v78
	v_readlane_b32 s47, v244, 47
	v_and_b32_e32 v0, 0x1f0, v0
	v_ashrrev_i32_e32 v9, 31, v8
	s_addc_u32 s7, s47, s9
	v_lshlrev_b64 v[10:11], 9, v[8:9]
	v_lshl_add_u64 v[12:13], s[6:7], 0, v[0:1]
	v_lshl_add_u64 v[2:3], v[12:13], 0, v[10:11]
	s_barrier
	global_load_dwordx4 v[172:175], v[2:3], off
	v_add_u32_e32 v6, 0, v0
	s_movk_i32 s46, 0x210
	v_mad_u64_u32 v[8:9], s[6:7], v8, s46, v[6:7]
	s_ashr_i32 s49, s48, 31
	v_and_b32_e32 v84, 15, v78
	v_ashrrev_i32_e32 v76, 6, v78
	v_bfe_u32 v79, v78, 4, 2
	v_mul_u32_u24_e32 v82, 0x210, v84
	v_add_u32_e32 v2, 0x200, v78
	v_ashrrev_i32_e32 v14, 5, v2
	v_ashrrev_i32_e32 v15, 31, v14
	v_lshlrev_b64 v[16:17], 9, v[14:15]
	v_lshl_add_u64 v[2:3], v[12:13], 0, v[16:17]
	global_load_dwordx4 v[176:179], v[2:3], off
	v_mad_u64_u32 v[14:15], s[6:7], v14, s46, v[6:7]
	v_add_u32_e32 v2, 0x400, v78
	v_ashrrev_i32_e32 v18, 5, v2
	v_ashrrev_i32_e32 v19, 31, v18
	v_lshlrev_b64 v[20:21], 9, v[18:19]
	v_lshl_add_u64 v[2:3], v[12:13], 0, v[20:21]
	global_load_dwordx4 v[180:183], v[2:3], off
	v_mad_u64_u32 v[18:19], s[6:7], v18, s46, v[6:7]
	v_add_u32_e32 v2, 0x600, v78
	v_ashrrev_i32_e32 v22, 5, v2
	v_ashrrev_i32_e32 v23, 31, v22
	v_lshlrev_b64 v[24:25], 9, v[22:23]
	v_lshl_add_u64 v[2:3], v[12:13], 0, v[24:25]
	global_load_dwordx4 v[184:187], v[2:3], off
	v_mad_u64_u32 v[6:7], s[6:7], v22, s46, v[6:7]
	s_lshl_b64 s[6:7], s[48:49], 15
	s_add_u32 s46, s40, s6
	s_addc_u32 s47, s47, s7
	v_lshl_add_u64 v[12:13], s[46:47], 0, v[0:1]
	v_lshlrev_b32_e32 v0, 8, v84
	s_mov_b64 s[46:47], 0
	v_lshl_add_u64 v[2:3], v[12:13], 0, v[10:11]
	global_load_dwordx4 v[188:191], v[2:3], off
	v_lshl_add_u64 v[2:3], v[12:13], 0, v[16:17]
	global_load_dwordx4 v[192:195], v[2:3], off
	v_lshl_add_u64 v[2:3], v[12:13], 0, v[20:21]
	global_load_dwordx4 v[196:199], v[2:3], off
	v_lshl_add_u64 v[2:3], v[12:13], 0, v[24:25]
	global_load_dwordx4 v[200:203], v[2:3], off
	v_lshl_or_b32 v2, v76, 13, v0
	v_ashrrev_i32_e32 v3, 31, v2
	v_lshlrev_b32_e32 v4, 4, v79
	v_lshlrev_b64 v[2:3], 1, v[2:3]
	v_or_b32_e32 v2, v2, v4
	v_lshl_add_u64 v[66:67], s[30:31], 0, v[2:3]
	v_add_co_u32_e32 v80, vcc, s87, v66
	s_nop 1
	v_addc_co_u32_e32 v81, vcc, 0, v67, vcc
	v_add_co_u32_e32 v102, vcc, s86, v66
	s_nop 1
	v_addc_co_u32_e32 v103, vcc, 0, v67, vcc
	global_load_dwordx4 v[104:107], v[80:81], off
	global_load_dwordx4 v[108:111], v[102:103], off
	global_load_dwordx4 v[112:115], v[80:81], off offset:64
	global_load_dwordx4 v[116:119], v[102:103], off offset:64
	global_load_dwordx4 v[120:123], v[80:81], off offset:128
	global_load_dwordx4 v[124:127], v[102:103], off offset:128
	global_load_dwordx4 v[128:131], v[80:81], off offset:192
	global_load_dwordx4 v[132:135], v[102:103], off offset:192
	global_load_dwordx4 v[140:143], v[80:81], off offset:256
	global_load_dwordx4 v[144:147], v[102:103], off offset:256
	global_load_dwordx4 v[148:151], v[80:81], off offset:320
	global_load_dwordx4 v[152:155], v[102:103], off offset:320
	global_load_dwordx4 v[156:159], v[80:81], off offset:384
	global_load_dwordx4 v[160:163], v[102:103], off offset:384
	global_load_dwordx4 v[164:167], v[80:81], off offset:448
	global_load_dwordx4 v[168:171], v[102:103], off offset:448
	s_waitcnt vmcnt(23)
	ds_write_b128 v8, v[172:175]
	s_waitcnt vmcnt(22)
	ds_write_b128 v14, v[176:179]
	s_waitcnt vmcnt(21)
	ds_write_b128 v18, v[180:183]
	s_waitcnt vmcnt(20)
	ds_write_b128 v6, v[184:187]
	s_waitcnt vmcnt(19)
	ds_write_b128 v8, v[188:191] offset:33792
	s_waitcnt vmcnt(18)
	ds_write_b128 v14, v[192:195] offset:33792
	s_waitcnt vmcnt(17)
	ds_write_b128 v18, v[196:199] offset:33792
	s_waitcnt vmcnt(16)
	ds_write_b128 v6, v[200:203] offset:33792
	v_mov_b32_e32 v2, 0
	v_add3_u32 v77, v82, v4, 0
	v_mov_b32_e32 v3, v2
	v_mov_b32_e32 v4, v2
	v_mov_b32_e32 v5, v2
	v_mov_b32_e32 v14, v2
	v_mov_b32_e32 v15, v2
	v_mov_b32_e32 v16, v2
	v_mov_b32_e32 v17, v2
	v_mov_b32_e32 v18, v2
	v_mov_b32_e32 v19, v2
	v_mov_b32_e32 v20, v2
	v_mov_b32_e32 v21, v2
	v_mov_b32_e32 v22, v2
	v_mov_b32_e32 v23, v2
	v_mov_b32_e32 v24, v2
	v_mov_b32_e32 v25, v2
	v_mov_b32_e32 v26, v2
	v_mov_b32_e32 v27, v2
	v_mov_b32_e32 v28, v2
	v_mov_b32_e32 v29, v2
	v_mov_b32_e32 v34, v2
	v_mov_b32_e32 v35, v2
	v_mov_b32_e32 v36, v2
	v_mov_b32_e32 v37, v2
	v_mov_b32_e32 v30, v2
	v_mov_b32_e32 v31, v2
	v_mov_b32_e32 v32, v2
	v_mov_b32_e32 v33, v2
	v_mov_b32_e32 v38, v2
	v_mov_b32_e32 v39, v2
	v_mov_b32_e32 v40, v2
	v_mov_b32_e32 v41, v2
	v_mov_b32_e32 v42, v2
	v_mov_b32_e32 v43, v2
	v_mov_b32_e32 v44, v2
	v_mov_b32_e32 v45, v2
	v_mov_b32_e32 v46, v2
	v_mov_b32_e32 v47, v2
	v_mov_b32_e32 v48, v2
	v_mov_b32_e32 v49, v2
	v_mov_b32_e32 v50, v2
	v_mov_b32_e32 v51, v2
	v_mov_b32_e32 v52, v2
	v_mov_b32_e32 v53, v2
	v_mov_b32_e32 v68, v2
	v_mov_b32_e32 v69, v2
	v_mov_b32_e32 v70, v2
	v_mov_b32_e32 v71, v2
	v_mov_b32_e32 v58, v2
	v_mov_b32_e32 v59, v2
	v_mov_b32_e32 v60, v2
	v_mov_b32_e32 v61, v2
	v_mov_b32_e32 v54, v2
	v_mov_b32_e32 v55, v2
	v_mov_b32_e32 v56, v2
	v_mov_b32_e32 v57, v2
	v_mov_b32_e32 v10, v2
	v_mov_b32_e32 v11, v2
	v_mov_b32_e32 v12, v2
	v_mov_b32_e32 v13, v2
	v_mov_b32_e32 v6, v2
	v_mov_b32_e32 v7, v2
	v_mov_b32_e32 v8, v2
	v_mov_b32_e32 v9, v2
	s_waitcnt lgkmcnt(0)
	s_barrier
; DI f32x4 mfma16(bf16x8 a, bf16x8 b, f32x4 c) { return __builtin_amdgcn_mfma_f32_16x16x32_bf16(a, b, c, 0, 0, 0); }
; template <int NT2>
; DI void glu_prologue(const Params& p, char* lds, int l, int tile0, int tile1) {
;     ...
; #pragma unroll 2
;     for (int ks = 0; ks < 8; ++ks) {
;         bf16x8 bb[2];
; #pragma unroll
;         for (int nt = 0; nt < 2; ++nt) bb[nt] = *(const bf16x8*)(Wg + (wid * 32 + nt * 16 + l15) * 256 + 32 * ks + 8 * quad);
; #pragma unroll
;         for (int tt = 0; tt < NT2; ++tt) {
;             const char* Ys = lds + tt * 33792;
;             bf16x8 a[4];
; #pragma unroll
;             for (int mt = 0; mt < 4; ++mt) a[mt] = *(const bf16x8*)(Ys + (mt * 16 + l15) * 528 + (32 * ks + 8 * quad) * 2);
; #pragma unroll
;             for (int mt = 0; mt < 4; ++mt)
; #pragma unroll
;                 for (int nt = 0; nt < 2; ++nt) acc[tt][mt][nt] = mfma16(bb[nt], a[mt], acc[tt][mt][nt]);
;         }
	s_waitcnt vmcnt(14)
	ds_read_b128 v[86:89], v77
	ds_read_b128 v[90:93], v77 offset:8448
	ds_read_b128 v[94:97], v77 offset:16896
	ds_read_b128 v[98:101], v77 offset:25344
	s_waitcnt lgkmcnt(3)
	v_mfma_f32_16x16x32_bf16 v[54:57], v[104:107], v[86:89], v[54:57]
	v_mfma_f32_16x16x32_bf16 v[58:61], v[108:111], v[86:89], v[58:61]
	s_waitcnt lgkmcnt(2)
	v_mfma_f32_16x16x32_bf16 v[68:71], v[104:107], v[90:93], v[68:71]
	v_mfma_f32_16x16x32_bf16 v[50:53], v[108:111], v[90:93], v[50:53]
	s_waitcnt lgkmcnt(1)
	v_mfma_f32_16x16x32_bf16 v[46:49], v[104:107], v[94:97], v[46:49]
	v_mfma_f32_16x16x32_bf16 v[42:45], v[108:111], v[94:97], v[42:45]
	s_waitcnt lgkmcnt(0)
	v_mfma_f32_16x16x32_bf16 v[38:41], v[104:107], v[98:101], v[38:41]
	v_mfma_f32_16x16x32_bf16 v[30:33], v[108:111], v[98:101], v[30:33]
	ds_read_b128 v[86:89], v77 offset:33792
	ds_read_b128 v[90:93], v77 offset:42240
	ds_read_b128 v[94:97], v77 offset:50688
	ds_read_b128 v[98:101], v77 offset:59136
	s_waitcnt lgkmcnt(3)
	v_mfma_f32_16x16x32_bf16 v[34:37], v[104:107], v[86:89], v[34:37]
	v_mfma_f32_16x16x32_bf16 v[26:29], v[108:111], v[86:89], v[26:29]
	s_waitcnt lgkmcnt(2)
	v_mfma_f32_16x16x32_bf16 v[22:25], v[104:107], v[90:93], v[22:25]
	v_mfma_f32_16x16x32_bf16 v[18:21], v[108:111], v[90:93], v[18:21]
	s_waitcnt lgkmcnt(1)
	v_mfma_f32_16x16x32_bf16 v[14:17], v[104:107], v[94:97], v[14:17]
	v_mfma_f32_16x16x32_bf16 v[2:5], v[108:111], v[94:97], v[2:5]
	s_waitcnt lgkmcnt(0)
	v_mfma_f32_16x16x32_bf16 v[10:13], v[104:107], v[98:101], v[10:13]
	v_mfma_f32_16x16x32_bf16 v[6:9], v[108:111], v[98:101], v[6:9]
	s_waitcnt vmcnt(12)
	ds_read_b128 v[86:89], v77 offset:64
	ds_read_b128 v[90:93], v77 offset:8512
	ds_read_b128 v[94:97], v77 offset:16960
	ds_read_b128 v[98:101], v77 offset:25408
	s_waitcnt lgkmcnt(3)
	v_mfma_f32_16x16x32_bf16 v[54:57], v[112:115], v[86:89], v[54:57]
	v_mfma_f32_16x16x32_bf16 v[58:61], v[116:119], v[86:89], v[58:61]
	s_waitcnt lgkmcnt(2)
	v_mfma_f32_16x16x32_bf16 v[68:71], v[112:115], v[90:93], v[68:71]
	v_mfma_f32_16x16x32_bf16 v[50:53], v[116:119], v[90:93], v[50:53]
	s_waitcnt lgkmcnt(1)
	v_mfma_f32_16x16x32_bf16 v[46:49], v[112:115], v[94:97], v[46:49]
	v_mfma_f32_16x16x32_bf16 v[42:45], v[116:119], v[94:97], v[42:45]
	s_waitcnt lgkmcnt(0)
	v_mfma_f32_16x16x32_bf16 v[38:41], v[112:115], v[98:101], v[38:41]
	v_mfma_f32_16x16x32_bf16 v[30:33], v[116:119], v[98:101], v[30:33]
	ds_read_b128 v[86:89], v77 offset:33856
	ds_read_b128 v[90:93], v77 offset:42304
	ds_read_b128 v[94:97], v77 offset:50752
	ds_read_b128 v[98:101], v77 offset:59200
	s_waitcnt lgkmcnt(3)
	v_mfma_f32_16x16x32_bf16 v[34:37], v[112:115], v[86:89], v[34:37]
	v_mfma_f32_16x16x32_bf16 v[26:29], v[116:119], v[86:89], v[26:29]
	s_waitcnt lgkmcnt(2)
	v_mfma_f32_16x16x32_bf16 v[22:25], v[112:115], v[90:93], v[22:25]
	v_mfma_f32_16x16x32_bf16 v[18:21], v[116:119], v[90:93], v[18:21]
	s_waitcnt lgkmcnt(1)
	v_mfma_f32_16x16x32_bf16 v[14:17], v[112:115], v[94:97], v[14:17]
	v_mfma_f32_16x16x32_bf16 v[2:5], v[116:119], v[94:97], v[2:5]
	s_waitcnt lgkmcnt(0)
	v_mfma_f32_16x16x32_bf16 v[10:13], v[112:115], v[98:101], v[10:13]
	v_mfma_f32_16x16x32_bf16 v[6:9], v[116:119], v[98:101], v[6:9]
	s_waitcnt vmcnt(10)
	ds_read_b128 v[86:89], v77 offset:128
	ds_read_b128 v[90:93], v77 offset:8576
	ds_read_b128 v[94:97], v77 offset:17024
	ds_read_b128 v[98:101], v77 offset:25472
	s_waitcnt lgkmcnt(3)
	v_mfma_f32_16x16x32_bf16 v[54:57], v[120:123], v[86:89], v[54:57]
	v_mfma_f32_16x16x32_bf16 v[58:61], v[124:127], v[86:89], v[58:61]
	s_waitcnt lgkmcnt(2)
	v_mfma_f32_16x16x32_bf16 v[68:71], v[120:123], v[90:93], v[68:71]
	v_mfma_f32_16x16x32_bf16 v[50:53], v[124:127], v[90:93], v[50:53]
	s_waitcnt lgkmcnt(1)
	v_mfma_f32_16x16x32_bf16 v[46:49], v[120:123], v[94:97], v[46:49]
	v_mfma_f32_16x16x32_bf16 v[42:45], v[124:127], v[94:97], v[42:45]
	s_waitcnt lgkmcnt(0)
	v_mfma_f32_16x16x32_bf16 v[38:41], v[120:123], v[98:101], v[38:41]
	v_mfma_f32_16x16x32_bf16 v[30:33], v[124:127], v[98:101], v[30:33]
	ds_read_b128 v[86:89], v77 offset:33920
	ds_read_b128 v[90:93], v77 offset:42368
	ds_read_b128 v[94:97], v77 offset:50816
	ds_read_b128 v[98:101], v77 offset:59264
	s_waitcnt lgkmcnt(3)
	v_mfma_f32_16x16x32_bf16 v[34:37], v[120:123], v[86:89], v[34:37]
	v_mfma_f32_16x16x32_bf16 v[26:29], v[124:127], v[86:89], v[26:29]
	s_waitcnt lgkmcnt(2)
	v_mfma_f32_16x16x32_bf16 v[22:25], v[120:123], v[90:93], v[22:25]
	v_mfma_f32_16x16x32_bf16 v[18:21], v[124:127], v[90:93], v[18:21]
	s_waitcnt lgkmcnt(1)
	v_mfma_f32_16x16x32_bf16 v[14:17], v[120:123], v[94:97], v[14:17]
	v_mfma_f32_16x16x32_bf16 v[2:5], v[124:127], v[94:97], v[2:5]
	s_waitcnt lgkmcnt(0)
	v_mfma_f32_16x16x32_bf16 v[10:13], v[120:123], v[98:101], v[10:13]
	v_mfma_f32_16x16x32_bf16 v[6:9], v[124:127], v[98:101], v[6:9]
	s_waitcnt vmcnt(8)
	ds_read_b128 v[86:89], v77 offset:192
	ds_read_b128 v[90:93], v77 offset:8640
	ds_read_b128 v[94:97], v77 offset:17088
	ds_read_b128 v[98:101], v77 offset:25536
	s_waitcnt lgkmcnt(3)
	v_mfma_f32_16x16x32_bf16 v[54:57], v[128:131], v[86:89], v[54:57]
	v_mfma_f32_16x16x32_bf16 v[58:61], v[132:135], v[86:89], v[58:61]
	s_waitcnt lgkmcnt(2)
	v_mfma_f32_16x16x32_bf16 v[68:71], v[128:131], v[90:93], v[68:71]
	v_mfma_f32_16x16x32_bf16 v[50:53], v[132:135], v[90:93], v[50:53]
	s_waitcnt lgkmcnt(1)
	v_mfma_f32_16x16x32_bf16 v[46:49], v[128:131], v[94:97], v[46:49]
	v_mfma_f32_16x16x32_bf16 v[42:45], v[132:135], v[94:97], v[42:45]
	s_waitcnt lgkmcnt(0)
	v_mfma_f32_16x16x32_bf16 v[38:41], v[128:131], v[98:101], v[38:41]
	v_mfma_f32_16x16x32_bf16 v[30:33], v[132:135], v[98:101], v[30:33]
	ds_read_b128 v[86:89], v77 offset:33984
	ds_read_b128 v[90:93], v77 offset:42432
	ds_read_b128 v[94:97], v77 offset:50880
	ds_read_b128 v[98:101], v77 offset:59328
	s_waitcnt lgkmcnt(3)
; DI f32x4 mfma16(bf16x8 a, bf16x8 b, f32x4 c) { return __builtin_amdgcn_mfma_f32_16x16x32_bf16(a, b, c, 0, 0, 0); }
; template <int NT2>
; DI void glu_prologue(const Params& p, char* lds, int l, int tile0, int tile1) {
;     ...
; #pragma unroll 2
;     for (int ks = 0; ks < 8; ++ks) {
;         bf16x8 bb[2];
; #pragma unroll
;         for (int nt = 0; nt < 2; ++nt) bb[nt] = *(const bf16x8*)(Wg + (wid * 32 + nt * 16 + l15) * 256 + 32 * ks + 8 * quad);
; #pragma unroll
;         for (int tt = 0; tt < NT2; ++tt) {
;             const char* Ys = lds + tt * 33792;
;             bf16x8 a[4];
; #pragma unroll
;             for (int mt = 0; mt < 4; ++mt) a[mt] = *(const bf16x8*)(Ys + (mt * 16 + l15) * 528 + (32 * ks + 8 * quad) * 2);
; #pragma unroll
;             for (int mt = 0; mt < 4; ++mt)
; #pragma unroll
;                 for (int nt = 0; nt < 2; ++nt) acc[tt][mt][nt] = mfma16(bb[nt], a[mt], acc[tt][mt][nt]);
;         }
	v_mfma_f32_16x16x32_bf16 v[34:37], v[128:131], v[86:89], v[34:37]
	v_mfma_f32_16x16x32_bf16 v[26:29], v[132:135], v[86:89], v[26:29]
	s_waitcnt lgkmcnt(2)
	v_mfma_f32_16x16x32_bf16 v[22:25], v[128:131], v[90:93], v[22:25]
	v_mfma_f32_16x16x32_bf16 v[18:21], v[132:135], v[90:93], v[18:21]
	s_waitcnt lgkmcnt(1)
	v_mfma_f32_16x16x32_bf16 v[14:17], v[128:131], v[94:97], v[14:17]
	v_mfma_f32_16x16x32_bf16 v[2:5], v[132:135], v[94:97], v[2:5]
	s_waitcnt lgkmcnt(0)
	v_mfma_f32_16x16x32_bf16 v[10:13], v[128:131], v[98:101], v[10:13]
	v_mfma_f32_16x16x32_bf16 v[6:9], v[132:135], v[98:101], v[6:9]
	s_waitcnt vmcnt(6)
	ds_read_b128 v[86:89], v77 offset:256
	ds_read_b128 v[90:93], v77 offset:8704
	ds_read_b128 v[94:97], v77 offset:17152
	ds_read_b128 v[98:101], v77 offset:25600
	s_waitcnt lgkmcnt(3)
	v_mfma_f32_16x16x32_bf16 v[54:57], v[140:143], v[86:89], v[54:57]
	v_mfma_f32_16x16x32_bf16 v[58:61], v[144:147], v[86:89], v[58:61]
	s_waitcnt lgkmcnt(2)
	v_mfma_f32_16x16x32_bf16 v[68:71], v[140:143], v[90:93], v[68:71]
	v_mfma_f32_16x16x32_bf16 v[50:53], v[144:147], v[90:93], v[50:53]
	s_waitcnt lgkmcnt(1)
	v_mfma_f32_16x16x32_bf16 v[46:49], v[140:143], v[94:97], v[46:49]
	v_mfma_f32_16x16x32_bf16 v[42:45], v[144:147], v[94:97], v[42:45]
	s_waitcnt lgkmcnt(0)
	v_mfma_f32_16x16x32_bf16 v[38:41], v[140:143], v[98:101], v[38:41]
	v_mfma_f32_16x16x32_bf16 v[30:33], v[144:147], v[98:101], v[30:33]
	ds_read_b128 v[86:89], v77 offset:34048
	ds_read_b128 v[90:93], v77 offset:42496
	ds_read_b128 v[94:97], v77 offset:50944
	ds_read_b128 v[98:101], v77 offset:59392
	s_waitcnt lgkmcnt(3)
	v_mfma_f32_16x16x32_bf16 v[34:37], v[140:143], v[86:89], v[34:37]
	v_mfma_f32_16x16x32_bf16 v[26:29], v[144:147], v[86:89], v[26:29]
	s_waitcnt lgkmcnt(2)
	v_mfma_f32_16x16x32_bf16 v[22:25], v[140:143], v[90:93], v[22:25]
	v_mfma_f32_16x16x32_bf16 v[18:21], v[144:147], v[90:93], v[18:21]
	s_waitcnt lgkmcnt(1)
	v_mfma_f32_16x16x32_bf16 v[14:17], v[140:143], v[94:97], v[14:17]
	v_mfma_f32_16x16x32_bf16 v[2:5], v[144:147], v[94:97], v[2:5]
	s_waitcnt lgkmcnt(0)
	v_mfma_f32_16x16x32_bf16 v[10:13], v[140:143], v[98:101], v[10:13]
	v_mfma_f32_16x16x32_bf16 v[6:9], v[144:147], v[98:101], v[6:9]
	s_waitcnt vmcnt(4)
	ds_read_b128 v[86:89], v77 offset:320
	ds_read_b128 v[90:93], v77 offset:8768
	ds_read_b128 v[94:97], v77 offset:17216
	ds_read_b128 v[98:101], v77 offset:25664
	s_waitcnt lgkmcnt(3)
	v_mfma_f32_16x16x32_bf16 v[54:57], v[148:151], v[86:89], v[54:57]
	v_mfma_f32_16x16x32_bf16 v[58:61], v[152:155], v[86:89], v[58:61]
	s_waitcnt lgkmcnt(2)
	v_mfma_f32_16x16x32_bf16 v[68:71], v[148:151], v[90:93], v[68:71]
	v_mfma_f32_16x16x32_bf16 v[50:53], v[152:155], v[90:93], v[50:53]
	s_waitcnt lgkmcnt(1)
	v_mfma_f32_16x16x32_bf16 v[46:49], v[148:151], v[94:97], v[46:49]
	v_mfma_f32_16x16x32_bf16 v[42:45], v[152:155], v[94:97], v[42:45]
	s_waitcnt lgkmcnt(0)
	v_mfma_f32_16x16x32_bf16 v[38:41], v[148:151], v[98:101], v[38:41]
	v_mfma_f32_16x16x32_bf16 v[30:33], v[152:155], v[98:101], v[30:33]
	ds_read_b128 v[86:89], v77 offset:34112
	ds_read_b128 v[90:93], v77 offset:42560
	ds_read_b128 v[94:97], v77 offset:51008
	ds_read_b128 v[98:101], v77 offset:59456
	s_waitcnt lgkmcnt(3)
	v_mfma_f32_16x16x32_bf16 v[34:37], v[148:151], v[86:89], v[34:37]
	v_mfma_f32_16x16x32_bf16 v[26:29], v[152:155], v[86:89], v[26:29]
	s_waitcnt lgkmcnt(2)
	v_mfma_f32_16x16x32_bf16 v[22:25], v[148:151], v[90:93], v[22:25]
	v_mfma_f32_16x16x32_bf16 v[18:21], v[152:155], v[90:93], v[18:21]
	s_waitcnt lgkmcnt(1)
	v_mfma_f32_16x16x32_bf16 v[14:17], v[148:151], v[94:97], v[14:17]
	v_mfma_f32_16x16x32_bf16 v[2:5], v[152:155], v[94:97], v[2:5]
	s_waitcnt lgkmcnt(0)
	v_mfma_f32_16x16x32_bf16 v[10:13], v[148:151], v[98:101], v[10:13]
	v_mfma_f32_16x16x32_bf16 v[6:9], v[152:155], v[98:101], v[6:9]
	s_waitcnt vmcnt(2)
	ds_read_b128 v[86:89], v77 offset:384
	ds_read_b128 v[90:93], v77 offset:8832
	ds_read_b128 v[94:97], v77 offset:17280
	ds_read_b128 v[98:101], v77 offset:25728
	s_waitcnt lgkmcnt(3)
	v_mfma_f32_16x16x32_bf16 v[54:57], v[156:159], v[86:89], v[54:57]
	v_mfma_f32_16x16x32_bf16 v[58:61], v[160:163], v[86:89], v[58:61]
	s_waitcnt lgkmcnt(2)
	v_mfma_f32_16x16x32_bf16 v[68:71], v[156:159], v[90:93], v[68:71]
	v_mfma_f32_16x16x32_bf16 v[50:53], v[160:163], v[90:93], v[50:53]
	s_waitcnt lgkmcnt(1)
	v_mfma_f32_16x16x32_bf16 v[46:49], v[156:159], v[94:97], v[46:49]
	v_mfma_f32_16x16x32_bf16 v[42:45], v[160:163], v[94:97], v[42:45]
	s_waitcnt lgkmcnt(0)
	v_mfma_f32_16x16x32_bf16 v[38:41], v[156:159], v[98:101], v[38:41]
	v_mfma_f32_16x16x32_bf16 v[30:33], v[160:163], v[98:101], v[30:33]
	ds_read_b128 v[86:89], v77 offset:34176
	ds_read_b128 v[90:93], v77 offset:42624
	ds_read_b128 v[94:97], v77 offset:51072
	ds_read_b128 v[98:101], v77 offset:59520
	s_waitcnt lgkmcnt(3)
	v_mfma_f32_16x16x32_bf16 v[34:37], v[156:159], v[86:89], v[34:37]
	v_mfma_f32_16x16x32_bf16 v[26:29], v[160:163], v[86:89], v[26:29]
	s_waitcnt lgkmcnt(2)
	v_mfma_f32_16x16x32_bf16 v[22:25], v[156:159], v[90:93], v[22:25]
	v_mfma_f32_16x16x32_bf16 v[18:21], v[160:163], v[90:93], v[18:21]
	s_waitcnt lgkmcnt(1)
	v_mfma_f32_16x16x32_bf16 v[14:17], v[156:159], v[94:97], v[14:17]
	v_mfma_f32_16x16x32_bf16 v[2:5], v[160:163], v[94:97], v[2:5]
	s_waitcnt lgkmcnt(0)
	v_mfma_f32_16x16x32_bf16 v[10:13], v[156:159], v[98:101], v[10:13]
	v_mfma_f32_16x16x32_bf16 v[6:9], v[160:163], v[98:101], v[6:9]
	s_waitcnt vmcnt(0)
	ds_read_b128 v[86:89], v77 offset:448
	ds_read_b128 v[90:93], v77 offset:8896
	ds_read_b128 v[94:97], v77 offset:17344
	ds_read_b128 v[98:101], v77 offset:25792
	s_waitcnt lgkmcnt(3)
; DI unsigned pk2(float lo, float hi) { const f32x2 v = {lo, hi}; const bf16x2_t b = __builtin_convertvector(v, bf16x2_t); return __builtin_bit_cast(unsigned, b); }
; DI float bf2f(unsigned b) { return __uint_as_float(b << 16); }
; DI float sigmoid_f(float x) { return __builtin_amdgcn_rcpf(1.f + __builtin_amdgcn_exp2f(x * -1.44269504089f)); }
; template <int NT2>
; DI void glu_prologue(const Params& p, char* lds, int l, int tile0, int tile1) {
;     ...
;     for (int ks = 0; ks < 8; ++ks) {
;         bf16x8 bb[2];
; #pragma unroll
;         for (int nt = 0; nt < 2; ++nt) bb[nt] = *(const bf16x8*)(Wg + (wid * 32 + nt * 16 + l15) * 256 + 32 * ks + 8 * quad);
; #pragma unroll
;         for (int tt = 0; tt < NT2; ++tt) {
;             const char* Ys = lds + tt * 33792;
;             bf16x8 a[4];
; #pragma unroll
;             for (int mt = 0; mt < 4; ++mt) a[mt] = *(const bf16x8*)(Ys + (mt * 16 + l15) * 528 + (32 * ks + 8 * quad) * 2);
; #pragma unroll
;             for (int mt = 0; mt < 4; ++mt)
; #pragma unroll
;                 for (int nt = 0; nt < 2; ++nt) acc[tt][mt][nt] = mfma16(bb[nt], a[mt], acc[tt][mt][nt]);
;     ...
; #pragma unroll
;     for (int tt = 0; tt < NT2; ++tt) {
;         const int tile = tt ? tile1 : tile0;
;         const char* Ys = lds + tt * 33792;
;         const bf16_t* sg = WS_PTR(const bf16_t, OFF_SG) + (size_t)tile * 64 * 256;
; #pragma unroll
;         for (int mt = 0; mt < 4; ++mt) {
;             const int tok = mt * 16 + l15;
; #pragma unroll
;             for (int nt = 0; nt < 2; ++nt) {
;                 const int n0 = wid * 32 + nt * 16 + quad * 4;
;                 const f32x4 gb = *(const f32x4*)(p.glu_b + l * 256 + n0);
;                 const u32x2 yv = *(const u32x2*)(Ys + tok * 528 + n0 * 2);
;                 const u32x2 sv = *(const u32x2*)(sg + (size_t)tok * 256 + n0);
;                 float o[4];
;                 o[0] = sigmoid_f(acc[tt][mt][nt][0] + gb[0]) * bf2f(yv[0] & 0xffffu) * bf2f(sv[0] & 0xffffu);
;                 o[1] = sigmoid_f(acc[tt][mt][nt][1] + gb[1]) * bf2f(yv[0] >> 16) * bf2f(sv[0] >> 16);
;                 o[2] = sigmoid_f(acc[tt][mt][nt][2] + gb[2]) * bf2f(yv[1] & 0xffffu) * bf2f(sv[1] & 0xffffu);
;                 o[3] = sigmoid_f(acc[tt][mt][nt][3] + gb[3]) * bf2f(yv[1] >> 16) * bf2f(sv[1] >> 16);
;                 *(u32x2*)(yo + y_off(tile * 64 + tok, 512 + n0)) = (u32x2){pk2(o[0], o[1]), pk2(o[2], o[3])};
	v_mfma_f32_16x16x32_bf16 v[54:57], v[164:167], v[86:89], v[54:57]
	v_mfma_f32_16x16x32_bf16 v[58:61], v[168:171], v[86:89], v[58:61]
	s_waitcnt lgkmcnt(2)
	v_mfma_f32_16x16x32_bf16 v[68:71], v[164:167], v[90:93], v[68:71]
	v_mfma_f32_16x16x32_bf16 v[50:53], v[168:171], v[90:93], v[50:53]
	s_waitcnt lgkmcnt(1)
	v_mfma_f32_16x16x32_bf16 v[46:49], v[164:167], v[94:97], v[46:49]
	v_mfma_f32_16x16x32_bf16 v[42:45], v[168:171], v[94:97], v[42:45]
	s_waitcnt lgkmcnt(0)
	v_mfma_f32_16x16x32_bf16 v[38:41], v[164:167], v[98:101], v[38:41]
	v_mfma_f32_16x16x32_bf16 v[30:33], v[168:171], v[98:101], v[30:33]
	ds_read_b128 v[86:89], v77 offset:34240
	ds_read_b128 v[90:93], v77 offset:42688
	ds_read_b128 v[94:97], v77 offset:51136
	ds_read_b128 v[98:101], v77 offset:59584
	s_waitcnt lgkmcnt(3)
	v_mfma_f32_16x16x32_bf16 v[34:37], v[164:167], v[86:89], v[34:37]
	v_mfma_f32_16x16x32_bf16 v[26:29], v[168:171], v[86:89], v[26:29]
	s_waitcnt lgkmcnt(2)
	v_mfma_f32_16x16x32_bf16 v[22:25], v[164:167], v[90:93], v[22:25]
	v_mfma_f32_16x16x32_bf16 v[18:21], v[168:171], v[90:93], v[18:21]
	s_waitcnt lgkmcnt(1)
	v_mfma_f32_16x16x32_bf16 v[14:17], v[164:167], v[94:97], v[14:17]
	v_mfma_f32_16x16x32_bf16 v[2:5], v[168:171], v[94:97], v[2:5]
	s_waitcnt lgkmcnt(0)
	v_mfma_f32_16x16x32_bf16 v[10:13], v[164:167], v[98:101], v[10:13]
	v_mfma_f32_16x16x32_bf16 v[6:9], v[168:171], v[98:101], v[6:9]
	v_lshlrev_b32_e32 v66, 5, v76
	v_lshlrev_b32_e32 v62, 2, v79
	v_or_b32_e32 v62, v62, v66
	v_ashrrev_i32_e32 v63, 31, v62
	v_lshl_add_u64 v[76:77], v[62:63], 2, s[2:3]
	global_load_dwordx4 v[216:219], v[76:77], off
	v_readlane_b32 s40, v244, 48
	s_add_u32 s8, s40, s8
	v_readlane_b32 s46, v244, 49
	s_addc_u32 s9, s46, s9
	v_lshlrev_b32_e32 v0, 1, v0
	v_lshl_add_u64 v[96:97], s[8:9], 0, v[0:1]
	v_lshlrev_b64 v[80:81], 1, v[62:63]
	v_lshl_add_u64 v[246:247], v[96:97], 0, v[80:81]
	global_load_dwordx2 v[224:225], v[246:247], off
	v_and_b32_e32 v63, 0xffffffc0, v78
	v_add_u32_e32 v86, 0x400, v63
	v_lshl_add_u32 v89, s34, 11, v86
	v_add_u32_e32 v87, 0, v82
	v_or_b32_e32 v82, v89, v84
	v_ashrrev_i32_e32 v63, 31, v66
	v_ashrrev_i32_e32 v83, 31, v82
	v_lshlrev_b32_e32 v90, 1, v62
	v_lshl_add_u64 v[72:73], v[62:63], 2, s[2:3]
	v_lshlrev_b64 v[74:75], 1, v[62:63]
	v_lshlrev_b64 v[62:63], 6, v[82:83]
	v_add_u32_e32 v64, v87, v90
	ds_read2st64_b64 v[64:67], v64 offset1:66
	v_lshlrev_b32_e32 v78, 3, v79
	v_mov_b32_e32 v79, v1
	v_lshl_add_u64 v[62:63], s[54:55], 0, v[62:63]
	v_lshl_add_u64 v[100:101], v[62:63], 0, v[78:79]
	s_waitcnt lgkmcnt(0)
	v_lshlrev_b32_e32 v62, 16, v64
	v_and_b32_e32 v63, 0xffff0000, v64
	v_lshlrev_b32_e32 v64, 16, v65
	v_and_b32_e32 v65, 0xffff0000, v65
	v_add_u32_e32 v91, 0x2100, v87
	s_add_u32 s6, s40, s6
	s_addc_u32 s7, s46, s7
	v_lshl_add_u64 v[246:247], v[96:97], 0, v[74:75]
	global_load_dwordx2 v[226:227], v[246:247], off offset:32
	s_waitcnt vmcnt(2)
	v_add_f32_e32 v54, v54, v216
	v_add_f32_e32 v55, v55, v217
	v_add_f32_e32 v56, v56, v218
	v_add_f32_e32 v57, v57, v219
	v_mul_f32_e32 v82, 0xbfb8aa3b, v54
	v_mul_f32_e32 v83, 0xbfb8aa3b, v55
	v_mul_f32_e32 v56, 0xbfb8aa3b, v56
	v_mul_f32_e32 v57, 0xbfb8aa3b, v57
	v_exp_f32_e32 v82, v82
	v_exp_f32_e32 v83, v83
	v_exp_f32_e32 v56, v56
	v_exp_f32_e32 v57, v57
	v_add_f32_e32 v82, 1.0, v82
	v_add_f32_e32 v83, 1.0, v83
	v_add_f32_e32 v85, 1.0, v56
	v_add_f32_e32 v88, 1.0, v57
	v_rcp_f32_e32 v56, v82
	v_rcp_f32_e32 v57, v83
	v_rcp_f32_e32 v82, v85
	v_rcp_f32_e32 v83, v88
	s_waitcnt vmcnt(1)
	v_lshlrev_b32_e32 v54, 16, v224
	v_and_b32_e32 v55, 0xffff0000, v224
	v_lshlrev_b32_e32 v92, 16, v225
	v_and_b32_e32 v93, 0xffff0000, v225
	v_pk_mul_f32 v[56:57], v[56:57], v[62:63]
	v_pk_mul_f32 v[62:63], v[82:83], v[64:65]
	v_pk_mul_f32 v[54:55], v[56:57], v[54:55]
	v_pk_mul_f32 v[56:57], v[62:63], v[92:93]
	v_cvt_pk_bf16_f32 v54, v54, v55
	v_cvt_pk_bf16_f32 v55, v56, v57
	global_store_dwordx2 v[100:101], v[54:55], off
	global_load_dwordx4 v[220:223], v[72:73], off offset:64
	v_or_b32_e32 v88, 32, v90
	v_add_u32_e32 v54, v87, v88
	ds_read2st64_b64 v[54:57], v54 offset1:66
	v_or_b32_e32 v85, 16, v84
	v_mov_b32_e32 v83, v1
	v_lshlrev_b32_e32 v82, 9, v85
	v_lshl_add_u64 v[94:95], s[8:9], 0, v[82:83]
	s_waitcnt lgkmcnt(0)
	v_lshlrev_b32_e32 v96, 16, v54
	v_and_b32_e32 v97, 0xffff0000, v54
	v_lshlrev_b32_e32 v54, 16, v55
	v_and_b32_e32 v55, 0xffff0000, v55
	v_lshl_add_u64 v[246:247], v[94:95], 0, v[80:81]
	global_load_dwordx2 v[224:225], v[246:247], off
	s_waitcnt vmcnt(1)
	v_add_f32_e32 v62, v58, v220
	v_add_f32_e32 v63, v59, v221
	v_add_f32_e32 v60, v60, v222
	v_add_f32_e32 v61, v61, v223
	v_mul_f32_e32 v62, 0xbfb8aa3b, v62
	v_mul_f32_e32 v63, 0xbfb8aa3b, v63
	v_mul_f32_e32 v60, 0xbfb8aa3b, v60
	v_mul_f32_e32 v61, 0xbfb8aa3b, v61
	v_exp_f32_e32 v62, v62
	v_exp_f32_e32 v63, v63
	v_exp_f32_e32 v60, v60
	v_exp_f32_e32 v61, v61
	v_add_f32_e32 v62, 1.0, v62
	v_add_f32_e32 v63, 1.0, v63
	v_add_f32_e32 v64, 1.0, v60
	v_add_f32_e32 v65, 1.0, v61
	v_rcp_f32_e32 v60, v62
	v_rcp_f32_e32 v61, v63
	v_rcp_f32_e32 v62, v64
	v_rcp_f32_e32 v63, v65
	s_waitcnt vmcnt(1)
	v_lshlrev_b32_e32 v58, 16, v226
	v_and_b32_e32 v59, 0xffff0000, v226
	v_lshlrev_b32_e32 v64, 16, v227
	v_and_b32_e32 v65, 0xffff0000, v227
	v_pk_mul_f32 v[60:61], v[60:61], v[96:97]
	v_pk_mul_f32 v[54:55], v[62:63], v[54:55]
	v_pk_mul_f32 v[58:59], v[60:61], v[58:59]
	v_pk_mul_f32 v[54:55], v[54:55], v[64:65]
	v_cvt_pk_bf16_f32 v58, v58, v59
	v_cvt_pk_bf16_f32 v59, v54, v55
	global_store_dwordx2 v[100:101], v[58:59], off offset:32
	v_add_u32_e32 v58, v91, v90
	ds_read2st64_b64 v[58:61], v58 offset1:66
	v_or_b32_e32 v92, v89, v85
	v_ashrrev_i32_e32 v93, 31, v92
	v_lshlrev_b64 v[92:93], 6, v[92:93]
	v_lshl_add_u64 v[92:93], s[54:55], 0, v[92:93]
	s_waitcnt lgkmcnt(0)
; DI unsigned pk2(float lo, float hi) { const f32x2 v = {lo, hi}; const bf16x2_t b = __builtin_convertvector(v, bf16x2_t); return __builtin_bit_cast(unsigned, b); }
; DI float bf2f(unsigned b) { return __uint_as_float(b << 16); }
; DI float sigmoid_f(float x) { return __builtin_amdgcn_rcpf(1.f + __builtin_amdgcn_exp2f(x * -1.44269504089f)); }
; DI size_t y_off(int tok, int col) { return ((size_t)(((tok >> 6) * 32 + (col >> 5)) * 64 + (tok & 63))) * 32 + (col & 31); }
; template <int NT2>
; DI void glu_prologue(const Params& p, char* lds, int l, int tile0, int tile1) {
;     ...
;     for (int tt = 0; tt < NT2; ++tt) {
;         const int tile = tt ? tile1 : tile0;
;         const char* Ys = lds + tt * 33792;
;         const bf16_t* sg = WS_PTR(const bf16_t, OFF_SG) + (size_t)tile * 64 * 256;
; #pragma unroll
;         for (int mt = 0; mt < 4; ++mt) {
;             const int tok = mt * 16 + l15;
; #pragma unroll
;             for (int nt = 0; nt < 2; ++nt) {
;                 const int n0 = wid * 32 + nt * 16 + quad * 4;
;                 const f32x4 gb = *(const f32x4*)(p.glu_b + l * 256 + n0);
;                 const u32x2 yv = *(const u32x2*)(Ys + tok * 528 + n0 * 2);
;                 const u32x2 sv = *(const u32x2*)(sg + (size_t)tok * 256 + n0);
;                 float o[4];
;                 o[0] = sigmoid_f(acc[tt][mt][nt][0] + gb[0]) * bf2f(yv[0] & 0xffffu) * bf2f(sv[0] & 0xffffu);
;                 o[1] = sigmoid_f(acc[tt][mt][nt][1] + gb[1]) * bf2f(yv[0] >> 16) * bf2f(sv[0] >> 16);
;                 o[2] = sigmoid_f(acc[tt][mt][nt][2] + gb[2]) * bf2f(yv[1] & 0xffffu) * bf2f(sv[1] & 0xffffu);
;                 o[3] = sigmoid_f(acc[tt][mt][nt][3] + gb[3]) * bf2f(yv[1] >> 16) * bf2f(sv[1] >> 16);
;                 *(u32x2*)(yo + y_off(tile * 64 + tok, 512 + n0)) = (u32x2){pk2(o[0], o[1]), pk2(o[2], o[3])};
	v_lshlrev_b32_e32 v96, 16, v58
	v_and_b32_e32 v97, 0xffff0000, v58
	v_lshlrev_b32_e32 v58, 16, v59
	v_and_b32_e32 v59, 0xffff0000, v59
	v_lshl_add_u64 v[92:93], v[92:93], 0, v[78:79]
	v_lshl_add_u64 v[246:247], v[94:95], 0, v[74:75]
	global_load_dwordx2 v[226:227], v[246:247], off offset:32
	v_add_f32_e32 v68, v68, v216
	v_add_f32_e32 v69, v69, v217
	s_waitcnt vmcnt(2)
	v_lshlrev_b32_e32 v62, 16, v224
	v_and_b32_e32 v63, 0xffff0000, v224
	v_add_f32_e32 v54, v70, v218
	v_add_f32_e32 v64, v71, v219
	v_mul_f32_e32 v65, 0xbfb8aa3b, v68
	v_mul_f32_e32 v68, 0xbfb8aa3b, v69
	v_mul_f32_e32 v54, 0xbfb8aa3b, v54
	v_mul_f32_e32 v64, 0xbfb8aa3b, v64
	v_exp_f32_e32 v65, v65
	v_exp_f32_e32 v68, v68
	v_exp_f32_e32 v54, v54
	v_exp_f32_e32 v64, v64
	v_add_f32_e32 v65, 1.0, v65
	v_add_f32_e32 v68, 1.0, v68
	v_add_f32_e32 v54, 1.0, v54
	v_add_f32_e32 v69, 1.0, v64
	v_rcp_f32_e32 v64, v65
	v_rcp_f32_e32 v65, v68
	v_rcp_f32_e32 v68, v54
	v_rcp_f32_e32 v69, v69
	v_lshlrev_b32_e32 v54, 16, v225
	v_and_b32_e32 v55, 0xffff0000, v225
	v_pk_mul_f32 v[64:65], v[64:65], v[96:97]
	v_pk_mul_f32 v[58:59], v[68:69], v[58:59]
	v_pk_mul_f32 v[62:63], v[64:65], v[62:63]
	v_pk_mul_f32 v[54:55], v[58:59], v[54:55]
	v_cvt_pk_bf16_f32 v58, v62, v63
	v_cvt_pk_bf16_f32 v59, v54, v55
	global_store_dwordx2 v[92:93], v[58:59], off
	v_add_u32_e32 v54, v91, v88
	ds_read2st64_b64 v[62:65], v54 offset1:66
	v_or_b32_e32 v58, 32, v84
	v_mov_b32_e32 v55, v1
	v_lshlrev_b32_e32 v54, 9, v58
	v_lshl_add_u64 v[96:97], s[8:9], 0, v[54:55]
	s_waitcnt lgkmcnt(0)
	v_lshlrev_b32_e32 v98, 16, v62
	v_and_b32_e32 v99, 0xffff0000, v62
	v_lshlrev_b32_e32 v62, 16, v63
	v_and_b32_e32 v63, 0xffff0000, v63
	v_lshl_add_u64 v[246:247], v[96:97], 0, v[80:81]
	global_load_dwordx2 v[224:225], v[246:247], off
	v_add_f32_e32 v59, v50, v220
	v_add_f32_e32 v68, v51, v221
	v_add_f32_e32 v52, v52, v222
	v_add_f32_e32 v53, v53, v223
	v_mul_f32_e32 v59, 0xbfb8aa3b, v59
	v_mul_f32_e32 v68, 0xbfb8aa3b, v68
	v_mul_f32_e32 v52, 0xbfb8aa3b, v52
	v_mul_f32_e32 v53, 0xbfb8aa3b, v53
	v_exp_f32_e32 v59, v59
	v_exp_f32_e32 v68, v68
	v_exp_f32_e32 v52, v52
	v_exp_f32_e32 v53, v53
	v_add_f32_e32 v59, 1.0, v59
	v_add_f32_e32 v68, 1.0, v68
	v_add_f32_e32 v69, 1.0, v52
	v_add_f32_e32 v70, 1.0, v53
	v_rcp_f32_e32 v52, v59
	v_rcp_f32_e32 v53, v68
	v_rcp_f32_e32 v68, v69
	v_rcp_f32_e32 v69, v70
	s_waitcnt vmcnt(2)
	v_lshlrev_b32_e32 v50, 16, v226
	v_and_b32_e32 v51, 0xffff0000, v226
	v_lshlrev_b32_e32 v70, 16, v227
	v_and_b32_e32 v71, 0xffff0000, v227
	v_pk_mul_f32 v[52:53], v[52:53], v[98:99]
	v_pk_mul_f32 v[62:63], v[68:69], v[62:63]
	v_pk_mul_f32 v[50:51], v[52:53], v[50:51]
	v_pk_mul_f32 v[52:53], v[62:63], v[70:71]
	v_cvt_pk_bf16_f32 v50, v50, v51
	v_cvt_pk_bf16_f32 v51, v52, v53
	global_store_dwordx2 v[92:93], v[50:51], off offset:32
	v_add_u32_e32 v59, 0x4200, v87
	v_add_u32_e32 v50, v59, v90
	ds_read2st64_b64 v[50:53], v50 offset1:66
	v_or_b32_e32 v92, v89, v58
	v_ashrrev_i32_e32 v93, 31, v92
	v_lshlrev_b64 v[92:93], 6, v[92:93]
	v_lshl_add_u64 v[92:93], s[54:55], 0, v[92:93]
	s_waitcnt lgkmcnt(0)
	v_lshlrev_b32_e32 v94, 16, v50
	v_and_b32_e32 v95, 0xffff0000, v50
	v_lshlrev_b32_e32 v50, 16, v51
	v_and_b32_e32 v51, 0xffff0000, v51
	v_lshl_add_u64 v[92:93], v[92:93], 0, v[78:79]
	v_add_u32_e32 v87, 0x6300, v87
	v_lshl_add_u64 v[246:247], v[96:97], 0, v[74:75]
	global_load_dwordx2 v[226:227], v[246:247], off offset:32
	v_add_f32_e32 v68, v46, v216
	v_add_f32_e32 v69, v47, v217
	v_add_f32_e32 v48, v48, v218
	v_add_f32_e32 v49, v49, v219
	s_waitcnt vmcnt(2)
	v_lshlrev_b32_e32 v46, 16, v224
	v_and_b32_e32 v47, 0xffff0000, v224
	v_mul_f32_e32 v62, 0xbfb8aa3b, v68
	v_mul_f32_e32 v68, 0xbfb8aa3b, v69
	v_mul_f32_e32 v48, 0xbfb8aa3b, v48
	v_mul_f32_e32 v49, 0xbfb8aa3b, v49
	v_exp_f32_e32 v62, v62
	v_exp_f32_e32 v68, v68
	v_exp_f32_e32 v48, v48
	v_exp_f32_e32 v49, v49
	v_add_f32_e32 v62, 1.0, v62
	v_add_f32_e32 v68, 1.0, v68
	v_add_f32_e32 v69, 1.0, v48
	v_add_f32_e32 v70, 1.0, v49
	v_rcp_f32_e32 v48, v62
	v_rcp_f32_e32 v49, v68
	v_rcp_f32_e32 v68, v69
	v_rcp_f32_e32 v69, v70
	v_lshlrev_b32_e32 v62, 16, v225
	v_and_b32_e32 v63, 0xffff0000, v225
	v_pk_mul_f32 v[48:49], v[48:49], v[94:95]
	v_pk_mul_f32 v[50:51], v[68:69], v[50:51]
	v_pk_mul_f32 v[46:47], v[48:49], v[46:47]
	v_pk_mul_f32 v[48:49], v[50:51], v[62:63]
	v_cvt_pk_bf16_f32 v46, v46, v47
	v_cvt_pk_bf16_f32 v47, v48, v49
	global_store_dwordx2 v[92:93], v[46:47], off
	v_add_u32_e32 v46, v59, v88
	ds_read2st64_b64 v[46:49], v46 offset1:66
	v_or_b32_e32 v59, 48, v84
	v_mov_b32_e32 v51, v1
	v_lshlrev_b32_e32 v50, 9, v59
	v_lshl_add_u64 v[94:95], s[8:9], 0, v[50:51]
	s_waitcnt lgkmcnt(0)
	v_lshlrev_b32_e32 v96, 16, v46
	v_and_b32_e32 v97, 0xffff0000, v46
	v_lshlrev_b32_e32 v46, 16, v47
	v_and_b32_e32 v47, 0xffff0000, v47
	v_lshl_add_u64 v[246:247], v[94:95], 0, v[80:81]
	global_load_dwordx2 v[224:225], v[246:247], off
	v_add_f32_e32 v68, v42, v220
	v_add_f32_e32 v69, v43, v221
	v_add_f32_e32 v44, v44, v222
	v_add_f32_e32 v45, v45, v223
	s_waitcnt vmcnt(2)
	v_lshlrev_b32_e32 v42, 16, v226
	v_and_b32_e32 v43, 0xffff0000, v226
	v_mul_f32_e32 v62, 0xbfb8aa3b, v68
	v_mul_f32_e32 v68, 0xbfb8aa3b, v69
	v_mul_f32_e32 v44, 0xbfb8aa3b, v44
	v_mul_f32_e32 v45, 0xbfb8aa3b, v45
	v_exp_f32_e32 v62, v62
	v_exp_f32_e32 v68, v68
	v_exp_f32_e32 v44, v44
	v_exp_f32_e32 v45, v45
	v_add_f32_e32 v62, 1.0, v62
	v_add_f32_e32 v68, 1.0, v68
	v_add_f32_e32 v69, 1.0, v44
	v_add_f32_e32 v70, 1.0, v45
	v_rcp_f32_e32 v44, v62
	v_rcp_f32_e32 v45, v68
	v_rcp_f32_e32 v68, v69
	v_rcp_f32_e32 v69, v70
	v_lshlrev_b32_e32 v62, 16, v227
	v_and_b32_e32 v63, 0xffff0000, v227
	v_pk_mul_f32 v[44:45], v[44:45], v[96:97]
	v_pk_mul_f32 v[46:47], v[68:69], v[46:47]
	v_pk_mul_f32 v[42:43], v[44:45], v[42:43]
	v_pk_mul_f32 v[44:45], v[46:47], v[62:63]
	v_cvt_pk_bf16_f32 v42, v42, v43
	v_cvt_pk_bf16_f32 v43, v44, v45
	global_store_dwordx2 v[92:93], v[42:43], off offset:32
	v_add_u32_e32 v42, v87, v90
	ds_read2st64_b64 v[42:45], v42 offset1:66
	v_or_b32_e32 v62, v89, v59
	v_ashrrev_i32_e32 v63, 31, v62
	v_lshlrev_b64 v[62:63], 6, v[62:63]
	v_lshl_add_u64 v[62:63], s[54:55], 0, v[62:63]
	s_waitcnt lgkmcnt(0)
; DI unsigned pk2(float lo, float hi) { const f32x2 v = {lo, hi}; const bf16x2_t b = __builtin_convertvector(v, bf16x2_t); return __builtin_bit_cast(unsigned, b); }
; DI float bf2f(unsigned b) { return __uint_as_float(b << 16); }
; DI float sigmoid_f(float x) { return __builtin_amdgcn_rcpf(1.f + __builtin_amdgcn_exp2f(x * -1.44269504089f)); }
; DI size_t y_off(int tok, int col) { return ((size_t)(((tok >> 6) * 32 + (col >> 5)) * 64 + (tok & 63))) * 32 + (col & 31); }
; template <int NT2>
; DI void glu_prologue(const Params& p, char* lds, int l, int tile0, int tile1) {
;     ...
;     for (int tt = 0; tt < NT2; ++tt) {
;         const int tile = tt ? tile1 : tile0;
;         const char* Ys = lds + tt * 33792;
;         const bf16_t* sg = WS_PTR(const bf16_t, OFF_SG) + (size_t)tile * 64 * 256;
; #pragma unroll
;         for (int mt = 0; mt < 4; ++mt) {
;             const int tok = mt * 16 + l15;
; #pragma unroll
;             for (int nt = 0; nt < 2; ++nt) {
;                 const int n0 = wid * 32 + nt * 16 + quad * 4;
;                 const f32x4 gb = *(const f32x4*)(p.glu_b + l * 256 + n0);
;                 const u32x2 yv = *(const u32x2*)(Ys + tok * 528 + n0 * 2);
;                 const u32x2 sv = *(const u32x2*)(sg + (size_t)tok * 256 + n0);
;                 float o[4];
;                 o[0] = sigmoid_f(acc[tt][mt][nt][0] + gb[0]) * bf2f(yv[0] & 0xffffu) * bf2f(sv[0] & 0xffffu);
;                 o[1] = sigmoid_f(acc[tt][mt][nt][1] + gb[1]) * bf2f(yv[0] >> 16) * bf2f(sv[0] >> 16);
;                 o[2] = sigmoid_f(acc[tt][mt][nt][2] + gb[2]) * bf2f(yv[1] & 0xffffu) * bf2f(sv[1] & 0xffffu);
;                 o[3] = sigmoid_f(acc[tt][mt][nt][3] + gb[3]) * bf2f(yv[1] >> 16) * bf2f(sv[1] >> 16);
;                 *(u32x2*)(yo + y_off(tile * 64 + tok, 512 + n0)) = (u32x2){pk2(o[0], o[1]), pk2(o[2], o[3])};
	v_lshlrev_b32_e32 v90, 16, v42
	v_and_b32_e32 v91, 0xffff0000, v42
	v_lshlrev_b32_e32 v42, 16, v43
	v_and_b32_e32 v43, 0xffff0000, v43
	v_lshl_add_u64 v[62:63], v[62:63], 0, v[78:79]
	v_lshl_add_u64 v[246:247], v[94:95], 0, v[74:75]
	global_load_dwordx2 v[226:227], v[246:247], off offset:32
	v_add_f32_e32 v68, v38, v216
	v_add_f32_e32 v69, v39, v217
	v_add_f32_e32 v40, v40, v218
	v_add_f32_e32 v41, v41, v219
	s_waitcnt vmcnt(2)
	v_lshlrev_b32_e32 v38, 16, v224
	v_and_b32_e32 v39, 0xffff0000, v224
	v_mul_f32_e32 v46, 0xbfb8aa3b, v68
	v_mul_f32_e32 v68, 0xbfb8aa3b, v69
	v_mul_f32_e32 v40, 0xbfb8aa3b, v40
	v_mul_f32_e32 v41, 0xbfb8aa3b, v41
	v_exp_f32_e32 v46, v46
	v_exp_f32_e32 v68, v68
	v_exp_f32_e32 v40, v40
	v_exp_f32_e32 v41, v41
	v_add_f32_e32 v46, 1.0, v46
	v_add_f32_e32 v68, 1.0, v68
	v_add_f32_e32 v69, 1.0, v40
	v_add_f32_e32 v70, 1.0, v41
	v_rcp_f32_e32 v40, v46
	v_rcp_f32_e32 v41, v68
	v_rcp_f32_e32 v68, v69
	v_rcp_f32_e32 v69, v70
	v_lshlrev_b32_e32 v46, 16, v225
	v_and_b32_e32 v47, 0xffff0000, v225
	v_pk_mul_f32 v[40:41], v[40:41], v[90:91]
	v_pk_mul_f32 v[42:43], v[68:69], v[42:43]
	v_pk_mul_f32 v[38:39], v[40:41], v[38:39]
	v_pk_mul_f32 v[40:41], v[42:43], v[46:47]
	v_cvt_pk_bf16_f32 v38, v38, v39
	v_cvt_pk_bf16_f32 v39, v40, v41
	global_store_dwordx2 v[62:63], v[38:39], off
	v_lshl_add_u64 v[46:47], s[6:7], 0, v[0:1]
	v_add_u32_e32 v38, v87, v88
	ds_read2st64_b64 v[38:41], v38 offset1:66
	s_waitcnt lgkmcnt(0)
	v_lshlrev_b32_e32 v88, 16, v38
	v_and_b32_e32 v89, 0xffff0000, v38
	v_lshlrev_b32_e32 v38, 16, v39
	v_and_b32_e32 v39, 0xffff0000, v39
	v_lshl_add_u64 v[246:247], v[46:47], 0, v[80:81]
	global_load_dwordx2 v[224:225], v[246:247], off
	v_add_f32_e32 v0, v30, v220
	v_add_f32_e32 v68, v31, v221
	v_add_f32_e32 v32, v32, v222
	v_add_f32_e32 v33, v33, v223
	s_waitcnt vmcnt(2)
	v_lshlrev_b32_e32 v30, 16, v226
	v_and_b32_e32 v31, 0xffff0000, v226
	v_mul_f32_e32 v0, 0xbfb8aa3b, v0
	v_mul_f32_e32 v42, 0xbfb8aa3b, v68
	v_mul_f32_e32 v32, 0xbfb8aa3b, v32
	v_mul_f32_e32 v33, 0xbfb8aa3b, v33
	v_exp_f32_e32 v0, v0
	v_exp_f32_e32 v42, v42
	v_exp_f32_e32 v32, v32
	v_exp_f32_e32 v33, v33
	v_add_f32_e32 v0, 1.0, v0
	v_add_f32_e32 v42, 1.0, v42
	v_add_f32_e32 v68, 1.0, v32
	v_add_f32_e32 v69, 1.0, v33
	v_rcp_f32_e32 v32, v0
	v_rcp_f32_e32 v33, v42
	v_rcp_f32_e32 v68, v68
	v_rcp_f32_e32 v69, v69
	v_lshlrev_b32_e32 v42, 16, v227
	v_and_b32_e32 v43, 0xffff0000, v227
	v_pk_mul_f32 v[32:33], v[32:33], v[88:89]
	v_pk_mul_f32 v[38:39], v[68:69], v[38:39]
	v_pk_mul_f32 v[30:31], v[32:33], v[30:31]
	v_pk_mul_f32 v[32:33], v[38:39], v[42:43]
	v_cvt_pk_bf16_f32 v30, v30, v31
	v_cvt_pk_bf16_f32 v31, v32, v33
	global_store_dwordx2 v[62:63], v[30:31], off offset:32
	v_lshl_add_u32 v0, s48, 11, v86
	v_or_b32_e32 v42, v0, v84
	v_ashrrev_i32_e32 v43, 31, v42
	v_lshlrev_b32_e32 v62, 16, v66
	v_and_b32_e32 v63, 0xffff0000, v66
	v_lshlrev_b32_e32 v66, 16, v67
	v_and_b32_e32 v67, 0xffff0000, v67
	v_lshlrev_b64 v[42:43], 6, v[42:43]
	v_lshl_add_u64 v[42:43], s[54:55], 0, v[42:43]
	v_lshl_add_u64 v[42:43], v[42:43], 0, v[78:79]
	v_lshl_add_u64 v[246:247], v[46:47], 0, v[74:75]
	global_load_dwordx2 v[226:227], v[246:247], off offset:32
	v_add_f32_e32 v34, v34, v216
	v_add_f32_e32 v35, v35, v217
	v_add_f32_e32 v32, v36, v218
	v_add_f32_e32 v33, v37, v219
	v_mul_f32_e32 v34, 0xbfb8aa3b, v34
	v_mul_f32_e32 v35, 0xbfb8aa3b, v35
	v_mul_f32_e32 v32, 0xbfb8aa3b, v32
	v_mul_f32_e32 v33, 0xbfb8aa3b, v33
	v_exp_f32_e32 v34, v34
	v_exp_f32_e32 v35, v35
	v_exp_f32_e32 v32, v32
	v_exp_f32_e32 v33, v33
	v_add_f32_e32 v34, 1.0, v34
	v_add_f32_e32 v35, 1.0, v35
	v_add_f32_e32 v36, 1.0, v32
	v_add_f32_e32 v37, 1.0, v33
	v_rcp_f32_e32 v32, v34
	v_rcp_f32_e32 v33, v35
	v_rcp_f32_e32 v34, v36
	v_rcp_f32_e32 v35, v37
	s_waitcnt vmcnt(2)
	v_lshlrev_b32_e32 v30, 16, v224
	v_and_b32_e32 v31, 0xffff0000, v224
	v_lshlrev_b32_e32 v36, 16, v225
	v_and_b32_e32 v37, 0xffff0000, v225
	v_pk_mul_f32 v[32:33], v[32:33], v[62:63]
	v_pk_mul_f32 v[34:35], v[34:35], v[66:67]
	v_pk_mul_f32 v[30:31], v[32:33], v[30:31]
	v_pk_mul_f32 v[32:33], v[34:35], v[36:37]
	v_cvt_pk_bf16_f32 v30, v30, v31
	v_cvt_pk_bf16_f32 v31, v32, v33
	global_store_dwordx2 v[42:43], v[30:31], off
	v_lshlrev_b32_e32 v38, 16, v56
	v_and_b32_e32 v39, 0xffff0000, v56
	v_lshlrev_b32_e32 v46, 16, v57
	v_and_b32_e32 v47, 0xffff0000, v57
	v_lshl_add_u64 v[36:37], s[6:7], 0, v[82:83]
	v_lshl_add_u64 v[246:247], v[36:37], 0, v[80:81]
	global_load_dwordx2 v[224:225], v[246:247], off
	v_add_f32_e32 v30, v26, v220
	v_add_f32_e32 v31, v27, v221
	v_add_f32_e32 v28, v28, v222
	v_add_f32_e32 v29, v29, v223
	v_mul_f32_e32 v30, 0xbfb8aa3b, v30
	v_mul_f32_e32 v31, 0xbfb8aa3b, v31
	v_mul_f32_e32 v28, 0xbfb8aa3b, v28
	v_mul_f32_e32 v29, 0xbfb8aa3b, v29
	v_exp_f32_e32 v30, v30
	v_exp_f32_e32 v31, v31
	v_exp_f32_e32 v28, v28
	v_exp_f32_e32 v29, v29
	v_add_f32_e32 v30, 1.0, v30
	v_add_f32_e32 v31, 1.0, v31
	v_add_f32_e32 v32, 1.0, v28
	v_add_f32_e32 v33, 1.0, v29
	v_rcp_f32_e32 v28, v30
	v_rcp_f32_e32 v29, v31
	v_rcp_f32_e32 v30, v32
	v_rcp_f32_e32 v31, v33
	s_waitcnt vmcnt(2)
; DI unsigned pk2(float lo, float hi) { const f32x2 v = {lo, hi}; const bf16x2_t b = __builtin_convertvector(v, bf16x2_t); return __builtin_bit_cast(unsigned, b); }
; DI float bf2f(unsigned b) { return __uint_as_float(b << 16); }
; DI float sigmoid_f(float x) { return __builtin_amdgcn_rcpf(1.f + __builtin_amdgcn_exp2f(x * -1.44269504089f)); }
; DI size_t y_off(int tok, int col) { return ((size_t)(((tok >> 6) * 32 + (col >> 5)) * 64 + (tok & 63))) * 32 + (col & 31); }
; template <int NT2>
; DI void glu_prologue(const Params& p, char* lds, int l, int tile0, int tile1) {
;     ...
;     for (int tt = 0; tt < NT2; ++tt) {
;         const int tile = tt ? tile1 : tile0;
;         const char* Ys = lds + tt * 33792;
;         const bf16_t* sg = WS_PTR(const bf16_t, OFF_SG) + (size_t)tile * 64 * 256;
; #pragma unroll
;         for (int mt = 0; mt < 4; ++mt) {
;             const int tok = mt * 16 + l15;
; #pragma unroll
;             for (int nt = 0; nt < 2; ++nt) {
;                 const int n0 = wid * 32 + nt * 16 + quad * 4;
;                 const f32x4 gb = *(const f32x4*)(p.glu_b + l * 256 + n0);
;                 const u32x2 yv = *(const u32x2*)(Ys + tok * 528 + n0 * 2);
;                 const u32x2 sv = *(const u32x2*)(sg + (size_t)tok * 256 + n0);
;                 float o[4];
;                 o[0] = sigmoid_f(acc[tt][mt][nt][0] + gb[0]) * bf2f(yv[0] & 0xffffu) * bf2f(sv[0] & 0xffffu);
;                 o[1] = sigmoid_f(acc[tt][mt][nt][1] + gb[1]) * bf2f(yv[0] >> 16) * bf2f(sv[0] >> 16);
;                 o[2] = sigmoid_f(acc[tt][mt][nt][2] + gb[2]) * bf2f(yv[1] & 0xffffu) * bf2f(sv[1] & 0xffffu);
;                 o[3] = sigmoid_f(acc[tt][mt][nt][3] + gb[3]) * bf2f(yv[1] >> 16) * bf2f(sv[1] >> 16);
;                 *(u32x2*)(yo + y_off(tile * 64 + tok, 512 + n0)) = (u32x2){pk2(o[0], o[1]), pk2(o[2], o[3])};
	v_lshlrev_b32_e32 v26, 16, v226
	v_and_b32_e32 v27, 0xffff0000, v226
	v_lshlrev_b32_e32 v32, 16, v227
	v_and_b32_e32 v33, 0xffff0000, v227
	v_pk_mul_f32 v[28:29], v[28:29], v[38:39]
	v_pk_mul_f32 v[30:31], v[30:31], v[46:47]
	v_pk_mul_f32 v[26:27], v[28:29], v[26:27]
	v_pk_mul_f32 v[28:29], v[30:31], v[32:33]
	v_cvt_pk_bf16_f32 v26, v26, v27
	v_cvt_pk_bf16_f32 v27, v28, v29
	global_store_dwordx2 v[42:43], v[26:27], off offset:32
	v_or_b32_e32 v32, v0, v85
	v_ashrrev_i32_e32 v33, 31, v32
	v_lshlrev_b32_e32 v34, 16, v60
	v_and_b32_e32 v35, 0xffff0000, v60
	v_lshlrev_b32_e32 v38, 16, v61
	v_and_b32_e32 v39, 0xffff0000, v61
	v_lshlrev_b64 v[32:33], 6, v[32:33]
	v_lshl_add_u64 v[32:33], s[54:55], 0, v[32:33]
	v_lshl_add_u64 v[32:33], v[32:33], 0, v[78:79]
	v_lshl_add_u64 v[246:247], v[36:37], 0, v[74:75]
	global_load_dwordx2 v[226:227], v[246:247], off offset:32
	v_add_f32_e32 v26, v22, v216
	v_add_f32_e32 v27, v23, v217
	v_add_f32_e32 v24, v24, v218
	v_add_f32_e32 v25, v25, v219
	v_mul_f32_e32 v26, 0xbfb8aa3b, v26
	v_mul_f32_e32 v27, 0xbfb8aa3b, v27
	v_mul_f32_e32 v24, 0xbfb8aa3b, v24
	v_mul_f32_e32 v25, 0xbfb8aa3b, v25
	v_exp_f32_e32 v26, v26
	v_exp_f32_e32 v27, v27
	v_exp_f32_e32 v24, v24
	v_exp_f32_e32 v25, v25
	v_add_f32_e32 v26, 1.0, v26
	v_add_f32_e32 v27, 1.0, v27
	v_add_f32_e32 v28, 1.0, v24
	v_add_f32_e32 v29, 1.0, v25
	v_rcp_f32_e32 v24, v26
	v_rcp_f32_e32 v25, v27
	v_rcp_f32_e32 v26, v28
	v_rcp_f32_e32 v27, v29
	s_waitcnt vmcnt(2)
	v_lshlrev_b32_e32 v22, 16, v224
	v_and_b32_e32 v23, 0xffff0000, v224
	v_lshlrev_b32_e32 v28, 16, v225
	v_and_b32_e32 v29, 0xffff0000, v225
	v_pk_mul_f32 v[24:25], v[24:25], v[34:35]
	v_pk_mul_f32 v[26:27], v[26:27], v[38:39]
	v_pk_mul_f32 v[22:23], v[24:25], v[22:23]
	v_pk_mul_f32 v[24:25], v[26:27], v[28:29]
	v_cvt_pk_bf16_f32 v22, v22, v23
	v_cvt_pk_bf16_f32 v23, v24, v25
	global_store_dwordx2 v[32:33], v[22:23], off
	v_lshlrev_b32_e32 v30, 16, v64
	v_and_b32_e32 v31, 0xffff0000, v64
	v_lshlrev_b32_e32 v34, 16, v65
	v_and_b32_e32 v35, 0xffff0000, v65
	v_lshl_add_u64 v[28:29], s[6:7], 0, v[54:55]
	v_lshl_add_u64 v[246:247], v[28:29], 0, v[80:81]
	global_load_dwordx2 v[224:225], v[246:247], off
	v_add_f32_e32 v22, v18, v220
	v_add_f32_e32 v23, v19, v221
	v_add_f32_e32 v20, v20, v222
	v_add_f32_e32 v21, v21, v223
	v_mul_f32_e32 v22, 0xbfb8aa3b, v22
	v_mul_f32_e32 v23, 0xbfb8aa3b, v23
	v_mul_f32_e32 v20, 0xbfb8aa3b, v20
	v_mul_f32_e32 v21, 0xbfb8aa3b, v21
	v_exp_f32_e32 v22, v22
	v_exp_f32_e32 v23, v23
	v_exp_f32_e32 v20, v20
	v_exp_f32_e32 v21, v21
	v_add_f32_e32 v22, 1.0, v22
	v_add_f32_e32 v23, 1.0, v23
	v_add_f32_e32 v24, 1.0, v20
	v_add_f32_e32 v25, 1.0, v21
	v_rcp_f32_e32 v20, v22
	v_rcp_f32_e32 v21, v23
	v_rcp_f32_e32 v22, v24
	v_rcp_f32_e32 v23, v25
	s_waitcnt vmcnt(2)
	v_lshlrev_b32_e32 v18, 16, v226
	v_and_b32_e32 v19, 0xffff0000, v226
	v_lshlrev_b32_e32 v24, 16, v227
	v_and_b32_e32 v25, 0xffff0000, v227
	v_pk_mul_f32 v[20:21], v[20:21], v[30:31]
	v_pk_mul_f32 v[22:23], v[22:23], v[34:35]
	v_pk_mul_f32 v[18:19], v[20:21], v[18:19]
	v_pk_mul_f32 v[20:21], v[22:23], v[24:25]
	v_cvt_pk_bf16_f32 v18, v18, v19
	v_cvt_pk_bf16_f32 v19, v20, v21
	global_store_dwordx2 v[32:33], v[18:19], off offset:32
	v_or_b32_e32 v24, v0, v58
	v_ashrrev_i32_e32 v25, 31, v24
	v_lshlrev_b32_e32 v26, 16, v52
	v_and_b32_e32 v27, 0xffff0000, v52
	v_lshlrev_b32_e32 v30, 16, v53
	v_and_b32_e32 v31, 0xffff0000, v53
	v_lshlrev_b64 v[24:25], 6, v[24:25]
	v_lshl_add_u64 v[24:25], s[54:55], 0, v[24:25]
	v_lshl_add_u64 v[24:25], v[24:25], 0, v[78:79]
	v_lshl_add_u64 v[246:247], v[28:29], 0, v[74:75]
	global_load_dwordx2 v[226:227], v[246:247], off offset:32
	v_add_f32_e32 v18, v14, v216
	v_add_f32_e32 v19, v15, v217
	v_add_f32_e32 v16, v16, v218
	v_add_f32_e32 v17, v17, v219
	v_mul_f32_e32 v18, 0xbfb8aa3b, v18
	v_mul_f32_e32 v19, 0xbfb8aa3b, v19
	v_mul_f32_e32 v16, 0xbfb8aa3b, v16
	v_mul_f32_e32 v17, 0xbfb8aa3b, v17
	v_exp_f32_e32 v18, v18
	v_exp_f32_e32 v19, v19
	v_exp_f32_e32 v16, v16
	v_exp_f32_e32 v17, v17
	v_add_f32_e32 v18, 1.0, v18
	v_add_f32_e32 v19, 1.0, v19
	v_add_f32_e32 v20, 1.0, v16
	v_add_f32_e32 v21, 1.0, v17
	v_rcp_f32_e32 v16, v18
	v_rcp_f32_e32 v17, v19
	v_rcp_f32_e32 v18, v20
	v_rcp_f32_e32 v19, v21
	s_waitcnt vmcnt(2)
; DI unsigned pk2(float lo, float hi) { const f32x2 v = {lo, hi}; const bf16x2_t b = __builtin_convertvector(v, bf16x2_t); return __builtin_bit_cast(unsigned, b); }
; DI float bf2f(unsigned b) { return __uint_as_float(b << 16); }
; DI float sigmoid_f(float x) { return __builtin_amdgcn_rcpf(1.f + __builtin_amdgcn_exp2f(x * -1.44269504089f)); }
; template <int N> DI void wait_vm() { asm volatile("s_waitcnt vmcnt(%0)" ::"n"(N) : "memory"); }
; DI size_t y_off(int tok, int col) { return ((size_t)(((tok >> 6) * 32 + (col >> 5)) * 64 + (tok & 63))) * 32 + (col & 31); }
; template <int NT2>
; DI void glu_prologue(const Params& p, char* lds, int l, int tile0, int tile1) {
;     ...
;     for (int tt = 0; tt < NT2; ++tt) {
;         const int tile = tt ? tile1 : tile0;
;         const char* Ys = lds + tt * 33792;
;         const bf16_t* sg = WS_PTR(const bf16_t, OFF_SG) + (size_t)tile * 64 * 256;
; #pragma unroll
;         for (int mt = 0; mt < 4; ++mt) {
;             const int tok = mt * 16 + l15;
; #pragma unroll
;             for (int nt = 0; nt < 2; ++nt) {
;                 const int n0 = wid * 32 + nt * 16 + quad * 4;
;                 const f32x4 gb = *(const f32x4*)(p.glu_b + l * 256 + n0);
;                 const u32x2 yv = *(const u32x2*)(Ys + tok * 528 + n0 * 2);
;                 const u32x2 sv = *(const u32x2*)(sg + (size_t)tok * 256 + n0);
;                 float o[4];
;                 o[0] = sigmoid_f(acc[tt][mt][nt][0] + gb[0]) * bf2f(yv[0] & 0xffffu) * bf2f(sv[0] & 0xffffu);
;                 o[1] = sigmoid_f(acc[tt][mt][nt][1] + gb[1]) * bf2f(yv[0] >> 16) * bf2f(sv[0] >> 16);
;                 o[2] = sigmoid_f(acc[tt][mt][nt][2] + gb[2]) * bf2f(yv[1] & 0xffffu) * bf2f(sv[1] & 0xffffu);
;                 o[3] = sigmoid_f(acc[tt][mt][nt][3] + gb[3]) * bf2f(yv[1] >> 16) * bf2f(sv[1] >> 16);
;                 *(u32x2*)(yo + y_off(tile * 64 + tok, 512 + n0)) = (u32x2){pk2(o[0], o[1]), pk2(o[2], o[3])};
;             }
;         }
;     }
;     wait_vm<0>();
	v_lshlrev_b32_e32 v14, 16, v224
	v_and_b32_e32 v15, 0xffff0000, v224
	v_lshlrev_b32_e32 v20, 16, v225
	v_and_b32_e32 v21, 0xffff0000, v225
	v_pk_mul_f32 v[16:17], v[16:17], v[26:27]
	v_pk_mul_f32 v[18:19], v[18:19], v[30:31]
	v_pk_mul_f32 v[14:15], v[16:17], v[14:15]
	v_pk_mul_f32 v[16:17], v[18:19], v[20:21]
	v_cvt_pk_bf16_f32 v14, v14, v15
	v_cvt_pk_bf16_f32 v15, v16, v17
	global_store_dwordx2 v[24:25], v[14:15], off
	v_lshlrev_b32_e32 v22, 16, v48
	v_and_b32_e32 v23, 0xffff0000, v48
	v_lshlrev_b32_e32 v26, 16, v49
	v_and_b32_e32 v27, 0xffff0000, v49
	v_lshl_add_u64 v[20:21], s[6:7], 0, v[50:51]
	v_lshl_add_u64 v[246:247], v[20:21], 0, v[80:81]
	global_load_dwordx2 v[224:225], v[246:247], off
	v_add_f32_e32 v14, v2, v220
	v_add_f32_e32 v15, v3, v221
	v_add_f32_e32 v4, v4, v222
	v_add_f32_e32 v5, v5, v223
	v_mul_f32_e32 v14, 0xbfb8aa3b, v14
	v_mul_f32_e32 v15, 0xbfb8aa3b, v15
	v_mul_f32_e32 v4, 0xbfb8aa3b, v4
	v_mul_f32_e32 v5, 0xbfb8aa3b, v5
	v_exp_f32_e32 v14, v14
	v_exp_f32_e32 v15, v15
	v_exp_f32_e32 v4, v4
	v_exp_f32_e32 v5, v5
	v_add_f32_e32 v14, 1.0, v14
	v_add_f32_e32 v15, 1.0, v15
	v_add_f32_e32 v16, 1.0, v4
	v_add_f32_e32 v17, 1.0, v5
	v_rcp_f32_e32 v4, v14
	v_rcp_f32_e32 v5, v15
	v_rcp_f32_e32 v14, v16
	v_rcp_f32_e32 v15, v17
	s_waitcnt vmcnt(2)
	v_lshlrev_b32_e32 v2, 16, v226
	v_and_b32_e32 v3, 0xffff0000, v226
	v_lshlrev_b32_e32 v16, 16, v227
	v_and_b32_e32 v17, 0xffff0000, v227
	v_pk_mul_f32 v[4:5], v[4:5], v[22:23]
	v_pk_mul_f32 v[14:15], v[14:15], v[26:27]
	v_pk_mul_f32 v[2:3], v[4:5], v[2:3]
	v_pk_mul_f32 v[4:5], v[14:15], v[16:17]
	v_cvt_pk_bf16_f32 v2, v2, v3
	v_cvt_pk_bf16_f32 v3, v4, v5
	global_store_dwordx2 v[24:25], v[2:3], off offset:32
	v_or_b32_e32 v16, v0, v59
	v_ashrrev_i32_e32 v17, 31, v16
	v_lshlrev_b32_e32 v18, 16, v44
	v_and_b32_e32 v19, 0xffff0000, v44
	v_lshlrev_b32_e32 v22, 16, v45
	v_and_b32_e32 v23, 0xffff0000, v45
	v_lshlrev_b64 v[16:17], 6, v[16:17]
	v_lshl_add_u64 v[16:17], s[54:55], 0, v[16:17]
	v_lshl_add_u64 v[16:17], v[16:17], 0, v[78:79]
	v_lshl_add_u64 v[246:247], v[20:21], 0, v[74:75]
	global_load_dwordx2 v[226:227], v[246:247], off offset:32
	v_add_f32_e32 v0, v10, v216
	v_add_f32_e32 v10, v11, v217
	v_add_f32_e32 v4, v12, v218
	v_add_f32_e32 v5, v13, v219
	v_mul_f32_e32 v0, 0xbfb8aa3b, v0
	v_mul_f32_e32 v10, 0xbfb8aa3b, v10
	v_mul_f32_e32 v4, 0xbfb8aa3b, v4
	v_mul_f32_e32 v5, 0xbfb8aa3b, v5
	v_exp_f32_e32 v0, v0
	v_exp_f32_e32 v10, v10
	v_exp_f32_e32 v4, v4
	v_exp_f32_e32 v5, v5
	v_add_f32_e32 v0, 1.0, v0
	v_add_f32_e32 v10, 1.0, v10
	v_add_f32_e32 v11, 1.0, v4
	v_add_f32_e32 v12, 1.0, v5
	v_rcp_f32_e32 v4, v0
	v_rcp_f32_e32 v5, v10
	v_rcp_f32_e32 v10, v11
	v_rcp_f32_e32 v11, v12
	s_waitcnt vmcnt(2)
	v_lshlrev_b32_e32 v2, 16, v224
	v_and_b32_e32 v3, 0xffff0000, v224
	v_lshlrev_b32_e32 v12, 16, v225
	v_and_b32_e32 v13, 0xffff0000, v225
	v_pk_mul_f32 v[4:5], v[4:5], v[18:19]
	v_pk_mul_f32 v[10:11], v[10:11], v[22:23]
	v_pk_mul_f32 v[2:3], v[4:5], v[2:3]
	v_pk_mul_f32 v[4:5], v[10:11], v[12:13]
	v_cvt_pk_bf16_f32 v2, v2, v3
	v_cvt_pk_bf16_f32 v3, v4, v5
	global_store_dwordx2 v[16:17], v[2:3], off
	v_lshlrev_b32_e32 v12, 16, v40
	v_and_b32_e32 v13, 0xffff0000, v40
	v_lshlrev_b32_e32 v14, 16, v41
	v_and_b32_e32 v15, 0xffff0000, v41
	v_add_f32_e32 v0, v6, v220
	v_add_f32_e32 v6, v7, v221
	v_add_f32_e32 v4, v8, v222
	v_add_f32_e32 v5, v9, v223
	v_mul_f32_e32 v0, 0xbfb8aa3b, v0
	v_mul_f32_e32 v6, 0xbfb8aa3b, v6
	v_mul_f32_e32 v4, 0xbfb8aa3b, v4
	v_mul_f32_e32 v5, 0xbfb8aa3b, v5
	v_exp_f32_e32 v0, v0
	v_exp_f32_e32 v6, v6
	v_exp_f32_e32 v4, v4
	v_exp_f32_e32 v5, v5
	v_add_f32_e32 v0, 1.0, v0
	v_add_f32_e32 v6, 1.0, v6
	v_add_f32_e32 v7, 1.0, v4
	v_add_f32_e32 v8, 1.0, v5
	v_rcp_f32_e32 v4, v0
	v_rcp_f32_e32 v5, v6
	v_rcp_f32_e32 v6, v7
	v_rcp_f32_e32 v7, v8
	s_waitcnt vmcnt(1)
	v_lshlrev_b32_e32 v2, 16, v226
	v_and_b32_e32 v3, 0xffff0000, v226
	v_lshlrev_b32_e32 v8, 16, v227
	v_and_b32_e32 v9, 0xffff0000, v227
	v_pk_mul_f32 v[4:5], v[4:5], v[12:13]
	v_pk_mul_f32 v[6:7], v[6:7], v[14:15]
	v_pk_mul_f32 v[2:3], v[4:5], v[2:3]
	v_pk_mul_f32 v[4:5], v[6:7], v[8:9]
	v_cvt_pk_bf16_f32 v2, v2, v3
	v_cvt_pk_bf16_f32 v3, v4, v5
	global_store_dwordx2 v[16:17], v[2:3], off offset:32
	s_waitcnt vmcnt(0)
